# LDS bank conflicts: sample-attention query tile moved to a free LDS region with 272-byte row pitch (4-way conflict on the q reads removed)
# speedup vs baseline: 1.0673x; 1.0133x over previous
; __device__ __forceinline__ void fox_sample_unit(const Params& p, int l, int b, int h, float* sf) {
;     ...
;     float *sQ = sf, *sS = sf + 1024, *sT = sf + 1024 + 16 * 1056, *sL = sT + 128 * 68;
;     const size_t rowq = (size_t)MP + b * 16;
;     for (int e = tid; e < 1024; e += 512) { const int t = e >> 6, d = e & 63; sQ[e] = bf2f(P[(rowq + t) * NP + PC_FQ + h * 64 + d]) * (0.125f * LOG2E); }
.LBB0_725:
	s_and_b64 vcc, exec, s[0:1]
	s_cbranch_vccz .LBB0_918
	s_add_i32 s9, s57, 0xfffffd80
	s_lshr_b32 s8, s9, 3
	s_lshl_b32 s0, s8, 4
	v_mov_b32_e32 v2, v190
	s_add_i32 s70, s0, 0x4000
	s_movk_i32 s0, 0x400
	s_nop 0
	v_cmp_gt_i32_e32 vcc, s0, v2
	s_lshl_b32 s0, s57, 6
	s_and_b32 s87, s0, 0x1c0
	s_and_saveexec_b64 s[0:1], vcc
	s_cbranch_execz .LBB0_734
	v_max_i32_e32 v3, 0x200, v2
	v_sub_u32_e32 v3, v3, v2
	v_and_b32_e32 v0, 63, v2
	v_add_u32_e32 v4, 0x1ff, v3
	v_cmp_lt_u32_e32 vcc, s41, v4
	s_mov_b64 s[4:5], -1
	v_lshlrev_b32_e32 v0, 1, v0
	v_mov_b32_e32 v3, v2
	s_and_saveexec_b64 s[2:3], vcc
	s_cbranch_execz .LBB0_731
	v_lshrrev_b32_e32 v3, 9, v4
	s_lshl_b32 s6, s87, 1
	v_readlane_b32 s10, v255, 34
	v_add_u32_e32 v8, 1, v3
	v_readlane_b32 s11, v255, 35
	s_add_u32 s6, s10, s6
	v_and_b32_e32 v9, 0xfffffe, v8
	v_add_u32_e32 v3, 0x200, v2
	s_addc_u32 s7, s11, 0
	s_mov_b32 s4, s70
	s_mov_b32 s5, s71
	v_lshl_add_u64 v[4:5], s[6:7], 0, v[0:1]
	v_lshrrev_b32_e32 v10, 6, v2
	v_mul_u32_u24_e32 v10, 0x110, v10
	v_lshl_add_u32 v10, v0, 1, v10
	v_add_u32_e32 v10, 0x1b000, v10
	s_mov_b64 s[6:7], 0
	v_mov_b32_e32 v11, v9
	v_mov_b64_e32 v[6:7], v[2:3]
.LBB0_729:
	v_ashrrev_i32_e32 v14, 6, v6
	v_ashrrev_i32_e32 v12, 6, v7
	v_ashrrev_i32_e32 v15, 31, v14
	v_ashrrev_i32_e32 v13, 31, v12
	v_lshl_add_u64 v[14:15], s[70:71], 0, v[14:15]
	v_lshl_add_u64 v[12:13], s[4:5], 0, v[12:13]
	v_mad_u64_u32 v[16:17], s[10:11], v14, s33, v[4:5]
	v_mad_i32_i24 v17, v15, s33, v17
	v_mad_u64_u32 v[14:15], s[10:11], v12, s33, v[4:5]
	v_mad_i32_i24 v15, v13, s33, v15
	global_load_ushort v3, v[16:17], off offset:3584
	global_load_ushort v12, v[14:15], off offset:3584
	v_add_u32_e32 v11, -2, v11
	v_cmp_eq_u32_e32 vcc, 0, v11
	v_add_u32_e32 v7, 0x400, v7
	v_add_u32_e32 v6, 0x400, v6
	s_or_b64 s[6:7], vcc, s[6:7]
	s_waitcnt vmcnt(0)
	v_lshlrev_b32_e32 v13, 16, v12
	v_lshlrev_b32_e32 v12, 16, v3
	v_pk_mul_f32 v[12:13], v[12:13], s[54:55] op_sel_hi:[1,0]
	ds_write_b32 v10, v12
	ds_write_b32 v10, v13 offset:2176
	v_add_u32_e32 v10, 0x1100, v10
	s_andn2_b64 exec, exec, s[6:7]
	s_cbranch_execnz .LBB0_729
	s_or_b64 exec, exec, s[6:7]
	v_cmp_ne_u32_e32 vcc, v8, v9
	v_lshl_add_u32 v3, v9, 9, v2
	s_orn2_b64 s[4:5], vcc, exec
.LBB0_731:
	s_or_b64 exec, exec, s[2:3]
	s_and_b64 exec, exec, s[4:5]
	s_cbranch_execz .LBB0_734
	s_lshl_b32 s2, s87, 1
	v_readlane_b32 s4, v255, 34
	v_readlane_b32 s5, v255, 35
	s_add_u32 s2, s4, s2
	s_addc_u32 s3, s5, 0
	v_lshl_add_u64 v[4:5], s[2:3], 0, v[0:1]
	v_lshrrev_b32_e32 v0, 6, v3
	v_mul_u32_u24_e32 v0, 0x110, v0
	v_and_b32_e32 v6, 63, v3
	v_lshl_add_u32 v0, v6, 2, v0
	v_add_u32_e32 v0, 0x1b000, v0
	s_mov_b64 s[2:3], 0
.LBB0_733:
	v_ashrrev_i32_e32 v6, 6, v3
	v_ashrrev_i32_e32 v7, 31, v6
	v_lshl_add_u64 v[6:7], v[6:7], 0, s[70:71]
	v_mad_u64_u32 v[8:9], s[4:5], v6, s33, v[4:5]
	v_mad_i32_i24 v9, v7, s33, v9
	global_load_ushort v6, v[8:9], off offset:3584
	v_add_u32_e32 v7, 0x200, v3
	v_cmp_lt_i32_e32 vcc, s41, v3
	s_or_b64 s[2:3], vcc, s[2:3]
	v_mov_b32_e32 v3, v7
	s_waitcnt vmcnt(0)
	v_lshlrev_b32_e32 v6, 16, v6
	v_mul_f32_e32 v6, 0x3e38aa3b, v6
	ds_write_b32 v0, v6
	v_add_u32_e32 v0, 0x880, v0
	s_andn2_b64 exec, exec, s[2:3]
	s_cbranch_execnz .LBB0_733
; __device__ __forceinline__ int otid() { int t = threadIdx.x; asm volatile("" : "+v"(t)); return t; }
; __device__ __forceinline__ void fox_sample_unit(const Params& p, int l, int b, int h, float* sf) {
;     const int tid = otid();
;     const bf16_t* P = (const bf16_t*)(p.ws + WS_P); const float* CKS = (const float*)(p.ws + WS_CKS) + (size_t)(b * 8 + h) * 1040; bf16_t* OB = (bf16_t*)(p.ws + WS_O) + (size_t)MT * 512;
;     float *sQ = sf, *sS = sf + 1024, *sT = sf + 1024 + 16 * 1056, *sL = sT + 128 * 68;
;     const size_t rowq = (size_t)MP + b * 16;
;     for (int e = tid; e < 1024; e += 512) { const int t = e >> 6, d = e & 63; sQ[e] = bf2f(P[(rowq + t) * NP + PC_FQ + h * 64 + d]) * (0.125f * LOG2E); }
;     for (int pass = 0; pass < 2; ++pass) {
;         const float* cache = p.in[pass ? I_CV : I_CK] + ((size_t)(l * 32 + b) * 1024) * 512 + h * 64;
;         const int pcol = (pass ? PC_FV : PC_FK) + h * 64;
;         float o0 = 0.f, o1 = 0.f;
;         f32x4 pre[4];
;     ...
;         SMP_LOAD(0);
;         for (int tile = 0; tile < 9; ++tile) {
;             const int nk = tile < 8 ? 128 : 16;
;             __syncthreads();
; #pragma unroll
;             for (int i = 0; i < 4; ++i) { const int e = tid + 512 * i, key = e >> 4, d4 = e & 15;
;                 if (key < nk) *(f32x4*)(sT + key * 68 + d4 * 4) = pre[i]; }
;             if (tile + 1 < 9) SMP_LOAD(tile + 1);
;             __syncthreads();
;             if (pass == 0) {
;                 const int key = tid >> 2, tq = tid & 3;
;                 if (key < nk) {
;                     float acc[4] = {0.f, 0.f, 0.f, 0.f};
; #pragma unroll 4
;                     for (int d4 = 0; d4 < 16; ++d4) { const f32x4 kv = *(const f32x4*)(sT + key * 68 + d4 * 4);
; #pragma unroll
;                         for (int i = 0; i < 4; ++i) { const f32x4 qv = *(const f32x4*)(sQ + (tq * 4 + i) * 64 + d4 * 4); acc[i] += (kv.x * qv.x + kv.y * qv.y) + (kv.z * qv.z + kv.w * qv.w); } }
;                     const int gkey = tile * 128 + key; const float bias = -CKS[gkey] * LOG2E;
; #pragma unroll
;                     for (int i = 0; i < 4; ++i) { const int t = tq * 4 + i; float s = acc[i] + bias; if (gkey > 1024 + t) s = -INFINITY; sS[t * 1056 + gkey] = s; }
.LBB0_734:
	s_or_b64 exec, exec, s[0:1]
	s_mul_i32 s0, s9, 0x410
	s_mov_b32 s1, s71
	s_lshl_b64 s[0:1], s[0:1], 2
	v_readlane_b32 s2, v255, 38
	s_add_u32 s0, s2, s0
	v_readlane_b32 s2, v255, 39
	s_addc_u32 s1, s2, s1
	s_add_i32 s2, s8, s74
	s_mov_b32 s3, s71
	v_lshlrev_b32_e32 v3, 2, v2
	s_lshl_b64 s[66:67], s[2:3], 21
	v_and_b32_e32 v4, 60, v3
	v_readlane_b32 s2, v255, 34
	v_lshlrev_b32_e32 v0, 1, v4
	v_readlane_b32 s3, v255, 35
	v_readlane_b32 s4, v255, 48
	v_ashrrev_i32_e32 v6, 5, v2
	v_lshl_add_u64 v[18:19], s[2:3], 0, v[0:1]
	v_lshlrev_b32_e32 v0, 1, v2
	v_and_b32_e32 v0, 62, v0
	s_movk_i32 s2, 0x1080
	v_lshl_add_u32 v5, v4, 2, s4
	v_mul_lo_u32 v106, v6, s2
	v_lshl_add_u32 v107, v0, 2, s4
	s_lshl_b32 s2, s87, 1
	v_readlane_b32 s4, v255, 40
	v_readlane_b32 s5, v255, 41
	s_add_u32 s2, s4, s2
	s_addc_u32 s3, s5, 0
	v_ashrrev_i32_e32 v7, 31, v6
	s_add_i32 s4, 0, 0x1a000
	v_lshl_add_u32 v109, v6, 2, s4
	v_lshl_add_u64 v[6:7], v[6:7], 0, s[70:71]
	v_lshlrev_b64 v[6:7], 10, v[6:7]
	v_lshl_add_u64 v[6:7], s[2:3], 0, v[6:7]
	v_lshlrev_b32_e32 v0, 1, v0
	v_lshl_add_u64 v[20:21], v[6:7], 0, v[0:1]
	v_ashrrev_i32_e32 v6, 4, v2
	v_ashrrev_i32_e32 v7, 31, v6
	v_add_u32_e32 v10, 0x200, v2
	v_add_u32_e32 v12, 0x400, v2
	v_add_u32_e32 v14, 0x600, v2
	v_ashrrev_i32_e32 v8, 2, v2
	v_and_b32_e32 v9, 3, v2
	v_lshlrev_b64 v[22:23], 11, v[6:7]
	v_ashrrev_i32_e32 v10, 4, v10
	v_ashrrev_i32_e32 v12, 4, v12
	v_ashrrev_i32_e32 v14, 4, v14
	v_lshl_add_u64 v[16:17], v[6:7], 0, s[70:71]
	v_bfrev_b32_e32 v7, 0.5
	v_lshl_add_u32 v108, v9, 10, 0
	v_mul_u32_u24_e32 v167, 0x440, v9
	v_add_u32_e32 v167, 0x1b000, v167
	v_lshlrev_b32_e32 v99, 2, v9
	v_and_b32_e32 v0, 31, v2
	v_ashrrev_i32_e32 v11, 31, v10
	v_ashrrev_i32_e32 v13, 31, v12
	v_ashrrev_i32_e32 v15, 31, v14
	v_bitop3_b32 v110, v3, 4, v7 bitop3:0x6c
	v_bitop3_b32 v111, v3, 8, v7 bitop3:0x6c
	v_bitop3_b32 v112, v3, 16, v7 bitop3:0x6c
	v_bitop3_b32 v113, v3, 32, v7 bitop3:0x6c
	v_bitop3_b32 v114, v3, 64, v7 bitop3:0x6c
	v_mul_u32_u24_e32 v3, 0x3e00, v9
	v_ashrrev_i32_e32 v9, 31, v8
	v_and_b32_e32 v2, -4, v2
	s_movk_i32 s6, 0x110
	v_lshlrev_b64 v[24:25], 11, v[10:11]
	v_lshlrev_b64 v[26:27], 11, v[12:13]
	v_lshlrev_b64 v[28:29], 11, v[14:15]
	v_lshl_add_u64 v[46:47], v[8:9], 2, s[0:1]
	v_add3_u32 v115, v108, v3, v2
	s_mov_b64 s[0:1], 0x80000
	v_or_b32_e32 v2, 1, v99
	v_mul_lo_u32 v98, v8, s6
	v_mul_lo_u32 v100, v6, s6
	v_mul_lo_u32 v101, v10, s6
	v_mul_lo_u32 v102, v12, s6
	v_mul_lo_u32 v103, v14, s6
	v_mad_u64_u32 v[30:31], s[6:7], v16, s33, 0
	v_lshl_add_u64 v[48:49], v[22:23], 0, s[0:1]
	v_lshl_add_u64 v[50:51], v[24:25], 0, s[0:1]
	v_lshl_add_u64 v[52:53], v[26:27], 0, s[0:1]
	v_lshl_add_u64 v[54:55], v[28:29], 0, s[0:1]
	s_mov_b64 s[0:1], 0xc0000
	v_cmp_gt_i32_e64 s[26:27], v8, v2
	v_or_b32_e32 v2, 2, v99
	v_mad_i32_i24 v31, v17, s33, v31
	v_lshl_add_u64 v[16:17], v[10:11], 0, s[70:71]
	v_lshl_add_u64 v[56:57], v[22:23], 0, s[0:1]
	v_lshl_add_u64 v[58:59], v[24:25], 0, s[0:1]
	v_lshl_add_u64 v[60:61], v[26:27], 0, s[0:1]
	v_lshl_add_u64 v[62:63], v[28:29], 0, s[0:1]
	s_mov_b64 s[0:1], 0x100000
	v_cmp_gt_i32_e64 s[28:29], v8, v2
	v_or_b32_e32 v2, 3, v99
	v_mad_u64_u32 v[32:33], s[8:9], v16, s33, 0
	v_lshl_add_u64 v[64:65], v[22:23], 0, s[0:1]
	v_lshl_add_u64 v[66:67], v[24:25], 0, s[0:1]
	v_lshl_add_u64 v[68:69], v[26:27], 0, s[0:1]
	v_lshl_add_u64 v[70:71], v[28:29], 0, s[0:1]
	s_mov_b64 s[0:1], 0x140000
	v_cmp_gt_i32_e64 s[30:31], v8, v2
	v_sub_u32_e32 v2, 0x40f, v0
	v_mad_i32_i24 v33, v17, s33, v33
	v_lshl_add_u64 v[16:17], v[12:13], 0, s[70:71]
	v_lshl_add_u64 v[72:73], v[22:23], 0, s[0:1]
	v_lshl_add_u64 v[74:75], v[24:25], 0, s[0:1]
	v_lshl_add_u64 v[76:77], v[26:27], 0, s[0:1]
	v_lshl_add_u64 v[78:79], v[28:29], 0, s[0:1]
	s_mov_b64 s[0:1], 0x180000
	v_lshrrev_b32_e32 v2, 5, v2
	v_mad_u64_u32 v[34:35], s[10:11], v16, s33, 0
	v_lshl_add_u64 v[80:81], v[22:23], 0, s[0:1]
	v_lshl_add_u64 v[82:83], v[24:25], 0, s[0:1]
	v_lshl_add_u64 v[84:85], v[26:27], 0, s[0:1]
	v_lshl_add_u64 v[86:87], v[28:29], 0, s[0:1]
	s_mov_b64 s[0:1], 0x1c0000
	v_add_u32_e32 v2, 1, v2
	v_mad_i32_i24 v35, v17, s33, v35
	v_lshl_add_u64 v[16:17], v[14:15], 0, s[70:71]
	v_lshl_add_u64 v[88:89], v[22:23], 0, s[0:1]
	v_lshl_add_u64 v[90:91], v[24:25], 0, s[0:1]
	v_lshl_add_u64 v[92:93], v[26:27], 0, s[0:1]
	v_lshl_add_u64 v[94:95], v[28:29], 0, s[0:1]
	s_mov_b64 s[0:1], 0x1000
	v_and_b32_e32 v116, 0x7e, v2
	v_mad_u64_u32 v[36:37], s[12:13], v16, s33, 0
	s_movk_i32 s20, 0x80
	s_mov_b64 s[22:23], 0x40000
	v_lshl_add_u64 v[96:97], v[46:47], 0, s[0:1]
	v_cmp_ne_u32_e64 s[34:35], v2, v116
	v_lshl_or_b32 v2, v0, 2, v106
	s_add_i32 s0, 0, 0x1000
	v_cmp_eq_u32_e64 s[2:3], 0, v0
	v_cmp_gt_i32_e64 s[4:5], 16, v6
	v_cmp_gt_i32_e64 s[6:7], 16, v10
	v_cmp_gt_i32_e64 s[8:9], 16, v12
	v_cmp_gt_i32_e64 s[10:11], 16, v14
	v_mad_i32_i24 v37, v17, s33, v37
	v_cmp_gt_i32_e64 s[12:13], s20, v6
	v_cmp_gt_i32_e64 s[14:15], s20, v10
	v_cmp_gt_i32_e64 s[16:17], s20, v12
	v_cmp_gt_i32_e64 s[18:19], s20, v14
	v_lshl_add_u64 v[38:39], v[22:23], 0, s[22:23]
	v_lshl_add_u64 v[40:41], v[24:25], 0, s[22:23]
	v_lshl_add_u64 v[42:43], v[26:27], 0, s[22:23]
	v_lshl_add_u64 v[44:45], v[28:29], 0, s[22:23]
	v_cmp_gt_i32_e64 s[20:21], s20, v8
	v_cmp_gt_i32_e64 s[22:23], 16, v8
	v_cmp_gt_i32_e64 s[24:25], v8, v99
	v_add_u32_e32 v117, 0x1000, v106
	v_lshlrev_b32_e32 v118, 3, v0
	v_add_u32_e32 v119, 0, v98
	v_add_u32_e32 v120, 0x1200, v106
	v_add_u32_e32 v121, 0x1400, v106
	v_add_u32_e32 v122, 0x1600, v106
	v_add_u32_e32 v123, 0x1800, v106
	v_add_u32_e32 v124, 0x1a00, v106
	v_add_u32_e32 v125, 0x1c00, v106
	v_add_u32_e32 v126, 0x1e00, v106
	v_add_u32_e32 v127, s0, v2
	v_or_b32_e32 v128, 0xffffffe0, v0
	s_mov_b64 s[68:69], -1
	v_lshlrev_b32_e32 v0, 2, v4
	v_add_u32_e32 v129, v5, v100
	v_add_u32_e32 v130, v5, v101
	v_add_u32_e32 v131, v5, v102
	v_add_u32_e32 v132, v5, v103
	s_branch .LBB0_737

; __device__ __forceinline__ void fox_sample_unit(const Params& p, int l, int b, int h, float* sf) {
;     ...
;                 const int key = tid >> 2, tq = tid & 3;
;                 if (key < nk) {
;                     float acc[4] = {0.f, 0.f, 0.f, 0.f};
; #pragma unroll 4
;                     for (int d4 = 0; d4 < 16; ++d4) { const f32x4 kv = *(const f32x4*)(sT + key * 68 + d4 * 4);
; #pragma unroll
;                         for (int i = 0; i < 4; ++i) { const f32x4 qv = *(const f32x4*)(sQ + (tq * 4 + i) * 64 + d4 * 4); acc[i] += (kv.x * qv.x + kv.y * qv.y) + (kv.z * qv.z + kv.w * qv.w); } }
;                     const int gkey = tile * 128 + key; const float bias = -CKS[gkey] * LOG2E;
; #pragma unroll
;                     for (int i = 0; i < 4; ++i) { const int t = tq * 4 + i; float s = acc[i] + bias; if (gkey > 1024 + t) s = -INFINITY; sS[t * 1056 + gkey] = s; }
.LBB0_749:
	v_add_u32_e32 v133, s58, v119
	v_add_u32_e32 v156, s58, v167
	v_add_u32_e32 v133, 0x11800, v133
	ds_read_b128 v[134:137], v133 offset:0
	ds_read_b128 v[138:141], v156 offset:0
	ds_read_b128 v[142:145], v156 offset:272
	ds_read_b128 v[146:149], v156 offset:544
	ds_read_b128 v[150:153], v156 offset:816
	ds_read_b128 v[158:161], v133 offset:16
	ds_read_b128 v[168:171], v156 offset:16
	ds_read_b128 v[172:175], v156 offset:288
	ds_read_b128 v[176:179], v156 offset:560
	ds_read_b128 v[180:183], v156 offset:832
	s_add_i32 s58, s58, 64
	s_cmpk_eq_i32 s58, 0x100
	s_waitcnt lgkmcnt(5)
	v_pk_fma_f32 v[104:105], v[134:135], v[138:139], v[104:105]
	v_pk_fma_f32 v[154:155], v[134:135], v[142:143], v[154:155]
	v_pk_fma_f32 v[184:185], v[134:135], v[146:147], v[184:185]
	v_pk_fma_f32 v[212:213], v[134:135], v[150:151], v[212:213]
	v_pk_fma_f32 v[104:105], v[136:137], v[140:141], v[104:105]
	v_pk_fma_f32 v[154:155], v[136:137], v[144:145], v[154:155]
	v_pk_fma_f32 v[184:185], v[136:137], v[148:149], v[184:185]
	v_pk_fma_f32 v[212:213], v[136:137], v[152:153], v[212:213]
	ds_read_b128 v[134:137], v133 offset:32
	ds_read_b128 v[138:141], v156 offset:32
	ds_read_b128 v[142:145], v156 offset:304
	ds_read_b128 v[146:149], v156 offset:576
	ds_read_b128 v[150:153], v156 offset:848
	s_waitcnt lgkmcnt(5)
	v_pk_fma_f32 v[104:105], v[158:159], v[168:169], v[104:105]
	v_pk_fma_f32 v[154:155], v[158:159], v[172:173], v[154:155]
	v_pk_fma_f32 v[184:185], v[158:159], v[176:177], v[184:185]
	v_pk_fma_f32 v[212:213], v[158:159], v[180:181], v[212:213]
	v_pk_fma_f32 v[104:105], v[160:161], v[170:171], v[104:105]
	v_pk_fma_f32 v[154:155], v[160:161], v[174:175], v[154:155]
	v_pk_fma_f32 v[184:185], v[160:161], v[178:179], v[184:185]
	v_pk_fma_f32 v[212:213], v[160:161], v[182:183], v[212:213]
	ds_read_b128 v[158:161], v133 offset:48
	ds_read_b128 v[168:171], v156 offset:48
	ds_read_b128 v[172:175], v156 offset:320
	ds_read_b128 v[176:179], v156 offset:592
	ds_read_b128 v[180:183], v156 offset:864
	s_waitcnt lgkmcnt(5)
	v_pk_fma_f32 v[104:105], v[134:135], v[138:139], v[104:105]
	v_pk_fma_f32 v[154:155], v[134:135], v[142:143], v[154:155]
	v_pk_fma_f32 v[184:185], v[134:135], v[146:147], v[184:185]
	v_pk_fma_f32 v[212:213], v[134:135], v[150:151], v[212:213]
	v_pk_fma_f32 v[104:105], v[136:137], v[140:141], v[104:105]
	v_pk_fma_f32 v[154:155], v[136:137], v[144:145], v[154:155]
	v_pk_fma_f32 v[184:185], v[136:137], v[148:149], v[184:185]
	v_pk_fma_f32 v[212:213], v[136:137], v[152:153], v[212:213]
	s_waitcnt lgkmcnt(0)
	v_pk_fma_f32 v[104:105], v[158:159], v[168:169], v[104:105]
	v_pk_fma_f32 v[154:155], v[158:159], v[172:173], v[154:155]
	v_pk_fma_f32 v[184:185], v[158:159], v[176:177], v[184:185]
	v_pk_fma_f32 v[212:213], v[158:159], v[180:181], v[212:213]
	v_pk_fma_f32 v[104:105], v[160:161], v[170:171], v[104:105]
	v_pk_fma_f32 v[154:155], v[160:161], v[174:175], v[154:155]
	v_pk_fma_f32 v[184:185], v[160:161], v[178:179], v[184:185]
	v_pk_fma_f32 v[212:213], v[160:161], v[182:183], v[212:213]
	s_cbranch_scc0 .LBB0_749
	s_nop 0
	v_add_f32_e32 v100, v104, v105
	v_add_f32_e32 v101, v154, v155
	v_add_f32_e32 v102, v184, v185
	v_add_f32_e32 v103, v212, v213
	global_load_dword v104, v[46:47], off
	s_waitcnt vmcnt(0)
	v_fmamk_f32 v100, v104, 0xbfb8aa3b, v100
	v_fmac_f32_e32 v101, 0xbfb8aa3b, v104
	v_fmamk_f32 v102, v104, 0xbfb8aa3b, v102
	v_fmac_f32_e32 v103, 0xbfb8aa3b, v104
	ds_write_b32 v115, v100 offset:4096
	ds_write_b32 v115, v101 offset:8320
	ds_write_b32 v115, v102 offset:12544
	ds_write_b32 v115, v103 offset:16768

; __device__ __forceinline__ void fox_sample_unit(const Params& p, int l, int b, int h, float* sf) {
;     ...
;                 const int key = tid >> 2, tq = tid & 3;
;                 if (key < nk) {
;                     float acc[4] = {0.f, 0.f, 0.f, 0.f};
; #pragma unroll 4
;                     for (int d4 = 0; d4 < 16; ++d4) { const f32x4 kv = *(const f32x4*)(sT + key * 68 + d4 * 4);
; #pragma unroll
;                         for (int i = 0; i < 4; ++i) { const f32x4 qv = *(const f32x4*)(sQ + (tq * 4 + i) * 64 + d4 * 4); acc[i] += (kv.x * qv.x + kv.y * qv.y) + (kv.z * qv.z + kv.w * qv.w); } }
;                     const int gkey = tile * 128 + key; const float bias = -CKS[gkey] * LOG2E;
; #pragma unroll
;                     for (int i = 0; i < 4; ++i) { const int t = tq * 4 + i; float s = acc[i] + bias; if (gkey > 1024 + t) s = -INFINITY; sS[t * 1056 + gkey] = s; }
.LBB0_761:
	s_and_b64 vcc, exec, s[82:83]
	s_cbranch_vccz .LBB0_767
	s_and_saveexec_b64 vcc, s[20:21]
	s_cbranch_execz .LBB0_766
	v_mov_b32_e32 v102, 0
	s_mov_b32 s58, 0
	v_mov_b32_e32 v103, v102
	v_mov_b32_e32 v104, v102
	v_mov_b32_e32 v105, v102
	v_mov_b32_e32 v180, 0
	v_mov_b32_e32 v181, 0
	v_mov_b32_e32 v182, 0
	v_mov_b32_e32 v183, 0
	v_mov_b32_e32 v184, 0
	v_mov_b32_e32 v185, 0
	v_mov_b32_e32 v212, 0
	v_mov_b32_e32 v213, 0
.LBB0_764:
	v_add_u32_e32 v133, s58, v119
	v_add_u32_e32 v166, s58, v167
	v_add_u32_e32 v133, 0x11800, v133
	ds_read_b128 v[134:137], v133 offset:0
	ds_read_b128 v[138:141], v166 offset:0
	ds_read_b128 v[142:145], v166 offset:272
	ds_read_b128 v[146:149], v166 offset:544
	ds_read_b128 v[150:153], v166 offset:816
	ds_read_b128 v[154:157], v133 offset:16
	ds_read_b128 v[158:161], v166 offset:16
	ds_read_b128 v[168:171], v166 offset:288
	ds_read_b128 v[172:175], v166 offset:560
	ds_read_b128 v[176:179], v166 offset:832
	s_add_i32 s58, s58, 64
	s_cmpk_lg_i32 s58, 0x100
	s_waitcnt lgkmcnt(5)
	v_pk_fma_f32 v[180:181], v[134:135], v[138:139], v[180:181]
	v_pk_fma_f32 v[182:183], v[134:135], v[142:143], v[182:183]
	v_pk_fma_f32 v[184:185], v[134:135], v[146:147], v[184:185]
	v_pk_fma_f32 v[212:213], v[134:135], v[150:151], v[212:213]
	v_pk_fma_f32 v[180:181], v[136:137], v[140:141], v[180:181]
	v_pk_fma_f32 v[182:183], v[136:137], v[144:145], v[182:183]
	v_pk_fma_f32 v[184:185], v[136:137], v[148:149], v[184:185]
	v_pk_fma_f32 v[212:213], v[136:137], v[152:153], v[212:213]
	ds_read_b128 v[134:137], v133 offset:32
	ds_read_b128 v[138:141], v166 offset:32
	ds_read_b128 v[142:145], v166 offset:304
	ds_read_b128 v[146:149], v166 offset:576
	ds_read_b128 v[150:153], v166 offset:848
	s_waitcnt lgkmcnt(5)
	v_pk_fma_f32 v[180:181], v[154:155], v[158:159], v[180:181]
	v_pk_fma_f32 v[182:183], v[154:155], v[168:169], v[182:183]
	v_pk_fma_f32 v[184:185], v[154:155], v[172:173], v[184:185]
	v_pk_fma_f32 v[212:213], v[154:155], v[176:177], v[212:213]
	v_pk_fma_f32 v[180:181], v[156:157], v[160:161], v[180:181]
	v_pk_fma_f32 v[182:183], v[156:157], v[170:171], v[182:183]
	v_pk_fma_f32 v[184:185], v[156:157], v[174:175], v[184:185]
	v_pk_fma_f32 v[212:213], v[156:157], v[178:179], v[212:213]
	ds_read_b128 v[154:157], v133 offset:48
	ds_read_b128 v[158:161], v166 offset:48
	ds_read_b128 v[168:171], v166 offset:320
	ds_read_b128 v[172:175], v166 offset:592
	ds_read_b128 v[176:179], v166 offset:864
	s_waitcnt lgkmcnt(5)
	v_pk_fma_f32 v[180:181], v[134:135], v[138:139], v[180:181]
	v_pk_fma_f32 v[182:183], v[134:135], v[142:143], v[182:183]
	v_pk_fma_f32 v[184:185], v[134:135], v[146:147], v[184:185]
	v_pk_fma_f32 v[212:213], v[134:135], v[150:151], v[212:213]
	v_pk_fma_f32 v[180:181], v[136:137], v[140:141], v[180:181]
	v_pk_fma_f32 v[182:183], v[136:137], v[144:145], v[182:183]
	v_pk_fma_f32 v[184:185], v[136:137], v[148:149], v[184:185]
	v_pk_fma_f32 v[212:213], v[136:137], v[152:153], v[212:213]
	s_waitcnt lgkmcnt(0)
	v_pk_fma_f32 v[180:181], v[154:155], v[158:159], v[180:181]
	v_pk_fma_f32 v[182:183], v[154:155], v[168:169], v[182:183]
	v_pk_fma_f32 v[184:185], v[154:155], v[172:173], v[184:185]
	v_pk_fma_f32 v[212:213], v[154:155], v[176:177], v[212:213]
	v_pk_fma_f32 v[180:181], v[156:157], v[160:161], v[180:181]
	v_pk_fma_f32 v[182:183], v[156:157], v[170:171], v[182:183]
	v_pk_fma_f32 v[184:185], v[156:157], v[174:175], v[184:185]
	v_pk_fma_f32 v[212:213], v[156:157], v[178:179], v[212:213]
	s_cbranch_scc1 .LBB0_764
	s_nop 0
	v_add_f32_e32 v102, v180, v181
	v_add_f32_e32 v103, v182, v183
	v_add_f32_e32 v104, v184, v185
	v_add_f32_e32 v105, v212, v213
	global_load_dword v133, v[46:47], off offset:512
	s_waitcnt vmcnt(0)
	v_fmamk_f32 v102, v133, 0xbfb8aa3b, v102
	v_fmac_f32_e32 v103, 0xbfb8aa3b, v133
	v_fmamk_f32 v104, v133, 0xbfb8aa3b, v104
	v_fmac_f32_e32 v105, 0xbfb8aa3b, v133
	ds_write_b32 v115, v102 offset:4608
	ds_write_b32 v115, v103 offset:8832
	ds_write_b32 v115, v104 offset:13056
	ds_write_b32 v115, v105 offset:17280

; __device__ __forceinline__ void fox_sample_unit(const Params& p, int l, int b, int h, float* sf) {
;     ...
;                 const int key = tid >> 2, tq = tid & 3;
;                 if (key < nk) {
;                     float acc[4] = {0.f, 0.f, 0.f, 0.f};
; #pragma unroll 4
;                     for (int d4 = 0; d4 < 16; ++d4) { const f32x4 kv = *(const f32x4*)(sT + key * 68 + d4 * 4);
; #pragma unroll
;                         for (int i = 0; i < 4; ++i) { const f32x4 qv = *(const f32x4*)(sQ + (tq * 4 + i) * 64 + d4 * 4); acc[i] += (kv.x * qv.x + kv.y * qv.y) + (kv.z * qv.z + kv.w * qv.w); } }
;                     const int gkey = tile * 128 + key; const float bias = -CKS[gkey] * LOG2E;
; #pragma unroll
;                     for (int i = 0; i < 4; ++i) { const int t = tq * 4 + i; float s = acc[i] + bias; if (gkey > 1024 + t) s = -INFINITY; sS[t * 1056 + gkey] = s; }
.LBB0_776:
	s_and_b64 vcc, exec, s[82:83]
	s_cbranch_vccz .LBB0_782
	s_and_saveexec_b64 vcc, s[20:21]
	s_cbranch_execz .LBB0_781
	v_mov_b32_e32 v100, 0
	s_mov_b32 s58, 0
	v_mov_b32_e32 v101, v100
	v_mov_b32_e32 v104, v100
	v_mov_b32_e32 v105, v100
	v_mov_b32_e32 v180, 0
	v_mov_b32_e32 v181, 0
	v_mov_b32_e32 v182, 0
	v_mov_b32_e32 v183, 0
	v_mov_b32_e32 v184, 0
	v_mov_b32_e32 v185, 0
	v_mov_b32_e32 v212, 0
	v_mov_b32_e32 v213, 0
.LBB0_779:
	v_add_u32_e32 v133, s58, v119
	v_add_u32_e32 v166, s58, v167
	v_add_u32_e32 v133, 0x11800, v133
	ds_read_b128 v[134:137], v133 offset:0
	ds_read_b128 v[138:141], v166 offset:0
	ds_read_b128 v[142:145], v166 offset:272
	ds_read_b128 v[146:149], v166 offset:544
	ds_read_b128 v[150:153], v166 offset:816
	ds_read_b128 v[154:157], v133 offset:16
	ds_read_b128 v[158:161], v166 offset:16
	ds_read_b128 v[168:171], v166 offset:288
	ds_read_b128 v[172:175], v166 offset:560
	ds_read_b128 v[176:179], v166 offset:832
	s_add_i32 s58, s58, 64
	s_cmpk_lg_i32 s58, 0x100
	s_waitcnt lgkmcnt(5)
	v_pk_fma_f32 v[180:181], v[134:135], v[138:139], v[180:181]
	v_pk_fma_f32 v[182:183], v[134:135], v[142:143], v[182:183]
	v_pk_fma_f32 v[184:185], v[134:135], v[146:147], v[184:185]
	v_pk_fma_f32 v[212:213], v[134:135], v[150:151], v[212:213]
	v_pk_fma_f32 v[180:181], v[136:137], v[140:141], v[180:181]
	v_pk_fma_f32 v[182:183], v[136:137], v[144:145], v[182:183]
	v_pk_fma_f32 v[184:185], v[136:137], v[148:149], v[184:185]
	v_pk_fma_f32 v[212:213], v[136:137], v[152:153], v[212:213]
	ds_read_b128 v[134:137], v133 offset:32
	ds_read_b128 v[138:141], v166 offset:32
	ds_read_b128 v[142:145], v166 offset:304
	ds_read_b128 v[146:149], v166 offset:576
	ds_read_b128 v[150:153], v166 offset:848
	s_waitcnt lgkmcnt(5)
	v_pk_fma_f32 v[180:181], v[154:155], v[158:159], v[180:181]
	v_pk_fma_f32 v[182:183], v[154:155], v[168:169], v[182:183]
	v_pk_fma_f32 v[184:185], v[154:155], v[172:173], v[184:185]
	v_pk_fma_f32 v[212:213], v[154:155], v[176:177], v[212:213]
	v_pk_fma_f32 v[180:181], v[156:157], v[160:161], v[180:181]
	v_pk_fma_f32 v[182:183], v[156:157], v[170:171], v[182:183]
	v_pk_fma_f32 v[184:185], v[156:157], v[174:175], v[184:185]
	v_pk_fma_f32 v[212:213], v[156:157], v[178:179], v[212:213]
	ds_read_b128 v[154:157], v133 offset:48
	ds_read_b128 v[158:161], v166 offset:48
	ds_read_b128 v[168:171], v166 offset:320
	ds_read_b128 v[172:175], v166 offset:592
	ds_read_b128 v[176:179], v166 offset:864
	s_waitcnt lgkmcnt(5)
	v_pk_fma_f32 v[180:181], v[134:135], v[138:139], v[180:181]
	v_pk_fma_f32 v[182:183], v[134:135], v[142:143], v[182:183]
	v_pk_fma_f32 v[184:185], v[134:135], v[146:147], v[184:185]
	v_pk_fma_f32 v[212:213], v[134:135], v[150:151], v[212:213]
	v_pk_fma_f32 v[180:181], v[136:137], v[140:141], v[180:181]
	v_pk_fma_f32 v[182:183], v[136:137], v[144:145], v[182:183]
	v_pk_fma_f32 v[184:185], v[136:137], v[148:149], v[184:185]
	v_pk_fma_f32 v[212:213], v[136:137], v[152:153], v[212:213]
	s_waitcnt lgkmcnt(0)
	v_pk_fma_f32 v[180:181], v[154:155], v[158:159], v[180:181]
	v_pk_fma_f32 v[182:183], v[154:155], v[168:169], v[182:183]
	v_pk_fma_f32 v[184:185], v[154:155], v[172:173], v[184:185]
	v_pk_fma_f32 v[212:213], v[154:155], v[176:177], v[212:213]
	v_pk_fma_f32 v[180:181], v[156:157], v[160:161], v[180:181]
	v_pk_fma_f32 v[182:183], v[156:157], v[170:171], v[182:183]
	v_pk_fma_f32 v[184:185], v[156:157], v[174:175], v[184:185]
	v_pk_fma_f32 v[212:213], v[156:157], v[178:179], v[212:213]
	s_cbranch_scc1 .LBB0_779
	s_nop 0
	v_add_f32_e32 v100, v180, v181
	v_add_f32_e32 v101, v182, v183
	v_add_f32_e32 v104, v184, v185
	v_add_f32_e32 v105, v212, v213
	global_load_dword v133, v[46:47], off offset:1024
	s_waitcnt vmcnt(0)
	v_fmamk_f32 v100, v133, 0xbfb8aa3b, v100
	v_fmac_f32_e32 v101, 0xbfb8aa3b, v133
	v_fmamk_f32 v104, v133, 0xbfb8aa3b, v104
	v_fmac_f32_e32 v105, 0xbfb8aa3b, v133
	ds_write_b32 v115, v100 offset:5120
	ds_write_b32 v115, v101 offset:9344
	ds_write_b32 v115, v104 offset:13568
	ds_write_b32 v115, v105 offset:17792

; __device__ __forceinline__ void fox_sample_unit(const Params& p, int l, int b, int h, float* sf) {
;     ...
;                 const int key = tid >> 2, tq = tid & 3;
;                 if (key < nk) {
;                     float acc[4] = {0.f, 0.f, 0.f, 0.f};
; #pragma unroll 4
;                     for (int d4 = 0; d4 < 16; ++d4) { const f32x4 kv = *(const f32x4*)(sT + key * 68 + d4 * 4);
; #pragma unroll
;                         for (int i = 0; i < 4; ++i) { const f32x4 qv = *(const f32x4*)(sQ + (tq * 4 + i) * 64 + d4 * 4); acc[i] += (kv.x * qv.x + kv.y * qv.y) + (kv.z * qv.z + kv.w * qv.w); } }
;                     const int gkey = tile * 128 + key; const float bias = -CKS[gkey] * LOG2E;
; #pragma unroll
;                     for (int i = 0; i < 4; ++i) { const int t = tq * 4 + i; float s = acc[i] + bias; if (gkey > 1024 + t) s = -INFINITY; sS[t * 1056 + gkey] = s; }
.LBB0_791:
	s_and_b64 vcc, exec, s[82:83]
	s_cbranch_vccz .LBB0_797
	s_and_saveexec_b64 vcc, s[20:21]
	s_cbranch_execz .LBB0_796
	v_mov_b32_e32 v100, 0
	s_mov_b32 s58, 0
	v_mov_b32_e32 v101, v100
	v_mov_b32_e32 v102, v100
	v_mov_b32_e32 v103, v100
	v_mov_b32_e32 v180, 0
	v_mov_b32_e32 v181, 0
	v_mov_b32_e32 v182, 0
	v_mov_b32_e32 v183, 0
	v_mov_b32_e32 v184, 0
	v_mov_b32_e32 v185, 0
	v_mov_b32_e32 v212, 0
	v_mov_b32_e32 v213, 0
.LBB0_794:
	v_add_u32_e32 v133, s58, v119
	v_add_u32_e32 v166, s58, v167
	v_add_u32_e32 v133, 0x11800, v133
	ds_read_b128 v[134:137], v133 offset:0
	ds_read_b128 v[138:141], v166 offset:0
	ds_read_b128 v[142:145], v166 offset:272
	ds_read_b128 v[146:149], v166 offset:544
	ds_read_b128 v[150:153], v166 offset:816
	ds_read_b128 v[154:157], v133 offset:16
	ds_read_b128 v[158:161], v166 offset:16
	ds_read_b128 v[168:171], v166 offset:288
	ds_read_b128 v[172:175], v166 offset:560
	ds_read_b128 v[176:179], v166 offset:832
	s_add_i32 s58, s58, 64
	s_cmpk_lg_i32 s58, 0x100
	s_waitcnt lgkmcnt(5)
	v_pk_fma_f32 v[180:181], v[134:135], v[138:139], v[180:181]
	v_pk_fma_f32 v[182:183], v[134:135], v[142:143], v[182:183]
	v_pk_fma_f32 v[184:185], v[134:135], v[146:147], v[184:185]
	v_pk_fma_f32 v[212:213], v[134:135], v[150:151], v[212:213]
	v_pk_fma_f32 v[180:181], v[136:137], v[140:141], v[180:181]
	v_pk_fma_f32 v[182:183], v[136:137], v[144:145], v[182:183]
	v_pk_fma_f32 v[184:185], v[136:137], v[148:149], v[184:185]
	v_pk_fma_f32 v[212:213], v[136:137], v[152:153], v[212:213]
	ds_read_b128 v[134:137], v133 offset:32
	ds_read_b128 v[138:141], v166 offset:32
	ds_read_b128 v[142:145], v166 offset:304
	ds_read_b128 v[146:149], v166 offset:576
	ds_read_b128 v[150:153], v166 offset:848
	s_waitcnt lgkmcnt(5)
	v_pk_fma_f32 v[180:181], v[154:155], v[158:159], v[180:181]
	v_pk_fma_f32 v[182:183], v[154:155], v[168:169], v[182:183]
	v_pk_fma_f32 v[184:185], v[154:155], v[172:173], v[184:185]
	v_pk_fma_f32 v[212:213], v[154:155], v[176:177], v[212:213]
	v_pk_fma_f32 v[180:181], v[156:157], v[160:161], v[180:181]
	v_pk_fma_f32 v[182:183], v[156:157], v[170:171], v[182:183]
	v_pk_fma_f32 v[184:185], v[156:157], v[174:175], v[184:185]
	v_pk_fma_f32 v[212:213], v[156:157], v[178:179], v[212:213]
	ds_read_b128 v[154:157], v133 offset:48
	ds_read_b128 v[158:161], v166 offset:48
	ds_read_b128 v[168:171], v166 offset:320
	ds_read_b128 v[172:175], v166 offset:592
	ds_read_b128 v[176:179], v166 offset:864
	s_waitcnt lgkmcnt(5)
	v_pk_fma_f32 v[180:181], v[134:135], v[138:139], v[180:181]
	v_pk_fma_f32 v[182:183], v[134:135], v[142:143], v[182:183]
	v_pk_fma_f32 v[184:185], v[134:135], v[146:147], v[184:185]
	v_pk_fma_f32 v[212:213], v[134:135], v[150:151], v[212:213]
	v_pk_fma_f32 v[180:181], v[136:137], v[140:141], v[180:181]
	v_pk_fma_f32 v[182:183], v[136:137], v[144:145], v[182:183]
	v_pk_fma_f32 v[184:185], v[136:137], v[148:149], v[184:185]
	v_pk_fma_f32 v[212:213], v[136:137], v[152:153], v[212:213]
	s_waitcnt lgkmcnt(0)
	v_pk_fma_f32 v[180:181], v[154:155], v[158:159], v[180:181]
	v_pk_fma_f32 v[182:183], v[154:155], v[168:169], v[182:183]
	v_pk_fma_f32 v[184:185], v[154:155], v[172:173], v[184:185]
	v_pk_fma_f32 v[212:213], v[154:155], v[176:177], v[212:213]
	v_pk_fma_f32 v[180:181], v[156:157], v[160:161], v[180:181]
	v_pk_fma_f32 v[182:183], v[156:157], v[170:171], v[182:183]
	v_pk_fma_f32 v[184:185], v[156:157], v[174:175], v[184:185]
	v_pk_fma_f32 v[212:213], v[156:157], v[178:179], v[212:213]
	s_cbranch_scc1 .LBB0_794
	s_nop 0
	v_add_f32_e32 v100, v180, v181
	v_add_f32_e32 v101, v182, v183
	v_add_f32_e32 v102, v184, v185
	v_add_f32_e32 v103, v212, v213
	global_load_dword v133, v[46:47], off offset:1536
	s_waitcnt vmcnt(0)
	v_fmamk_f32 v100, v133, 0xbfb8aa3b, v100
	v_fmac_f32_e32 v101, 0xbfb8aa3b, v133
	v_fmamk_f32 v102, v133, 0xbfb8aa3b, v102
	v_fmac_f32_e32 v103, 0xbfb8aa3b, v133
	ds_write_b32 v115, v100 offset:5632
	ds_write_b32 v115, v101 offset:9856
	ds_write_b32 v115, v102 offset:14080
	ds_write_b32 v115, v103 offset:18304

; __device__ __forceinline__ void fox_sample_unit(const Params& p, int l, int b, int h, float* sf) {
;     ...
;                 const int key = tid >> 2, tq = tid & 3;
;                 if (key < nk) {
;                     float acc[4] = {0.f, 0.f, 0.f, 0.f};
; #pragma unroll 4
;                     for (int d4 = 0; d4 < 16; ++d4) { const f32x4 kv = *(const f32x4*)(sT + key * 68 + d4 * 4);
; #pragma unroll
;                         for (int i = 0; i < 4; ++i) { const f32x4 qv = *(const f32x4*)(sQ + (tq * 4 + i) * 64 + d4 * 4); acc[i] += (kv.x * qv.x + kv.y * qv.y) + (kv.z * qv.z + kv.w * qv.w); } }
;                     const int gkey = tile * 128 + key; const float bias = -CKS[gkey] * LOG2E;
; #pragma unroll
;                     for (int i = 0; i < 4; ++i) { const int t = tq * 4 + i; float s = acc[i] + bias; if (gkey > 1024 + t) s = -INFINITY; sS[t * 1056 + gkey] = s; }
.LBB0_809:
	v_add_u32_e32 v133, s58, v119
	v_add_u32_e32 v166, s58, v167
	v_add_u32_e32 v133, 0x11800, v133
	ds_read_b128 v[134:137], v133 offset:0
	ds_read_b128 v[138:141], v166 offset:0
	ds_read_b128 v[142:145], v166 offset:272
	ds_read_b128 v[146:149], v166 offset:544
	ds_read_b128 v[150:153], v166 offset:816
	ds_read_b128 v[154:157], v133 offset:16
	ds_read_b128 v[158:161], v166 offset:16
	ds_read_b128 v[168:171], v166 offset:288
	ds_read_b128 v[172:175], v166 offset:560
	ds_read_b128 v[176:179], v166 offset:832
	s_add_i32 s58, s58, 64
	s_cmpk_lg_i32 s58, 0x100
	s_waitcnt lgkmcnt(5)
	v_pk_fma_f32 v[180:181], v[134:135], v[138:139], v[180:181]
	v_pk_fma_f32 v[182:183], v[134:135], v[142:143], v[182:183]
	v_pk_fma_f32 v[184:185], v[134:135], v[146:147], v[184:185]
	v_pk_fma_f32 v[212:213], v[134:135], v[150:151], v[212:213]
	v_pk_fma_f32 v[180:181], v[136:137], v[140:141], v[180:181]
	v_pk_fma_f32 v[182:183], v[136:137], v[144:145], v[182:183]
	v_pk_fma_f32 v[184:185], v[136:137], v[148:149], v[184:185]
	v_pk_fma_f32 v[212:213], v[136:137], v[152:153], v[212:213]
	ds_read_b128 v[134:137], v133 offset:32
	ds_read_b128 v[138:141], v166 offset:32
	ds_read_b128 v[142:145], v166 offset:304
	ds_read_b128 v[146:149], v166 offset:576
	ds_read_b128 v[150:153], v166 offset:848
	s_waitcnt lgkmcnt(5)
	v_pk_fma_f32 v[180:181], v[154:155], v[158:159], v[180:181]
	v_pk_fma_f32 v[182:183], v[154:155], v[168:169], v[182:183]
	v_pk_fma_f32 v[184:185], v[154:155], v[172:173], v[184:185]
	v_pk_fma_f32 v[212:213], v[154:155], v[176:177], v[212:213]
	v_pk_fma_f32 v[180:181], v[156:157], v[160:161], v[180:181]
	v_pk_fma_f32 v[182:183], v[156:157], v[170:171], v[182:183]
	v_pk_fma_f32 v[184:185], v[156:157], v[174:175], v[184:185]
	v_pk_fma_f32 v[212:213], v[156:157], v[178:179], v[212:213]
	ds_read_b128 v[154:157], v133 offset:48
	ds_read_b128 v[158:161], v166 offset:48
	ds_read_b128 v[168:171], v166 offset:320
	ds_read_b128 v[172:175], v166 offset:592
	ds_read_b128 v[176:179], v166 offset:864
	s_waitcnt lgkmcnt(5)
	v_pk_fma_f32 v[180:181], v[134:135], v[138:139], v[180:181]
	v_pk_fma_f32 v[182:183], v[134:135], v[142:143], v[182:183]
	v_pk_fma_f32 v[184:185], v[134:135], v[146:147], v[184:185]
	v_pk_fma_f32 v[212:213], v[134:135], v[150:151], v[212:213]
	v_pk_fma_f32 v[180:181], v[136:137], v[140:141], v[180:181]
	v_pk_fma_f32 v[182:183], v[136:137], v[144:145], v[182:183]
	v_pk_fma_f32 v[184:185], v[136:137], v[148:149], v[184:185]
	v_pk_fma_f32 v[212:213], v[136:137], v[152:153], v[212:213]
	s_waitcnt lgkmcnt(0)
	v_pk_fma_f32 v[180:181], v[154:155], v[158:159], v[180:181]
	v_pk_fma_f32 v[182:183], v[154:155], v[168:169], v[182:183]
	v_pk_fma_f32 v[184:185], v[154:155], v[172:173], v[184:185]
	v_pk_fma_f32 v[212:213], v[154:155], v[176:177], v[212:213]
	v_pk_fma_f32 v[180:181], v[156:157], v[160:161], v[180:181]
	v_pk_fma_f32 v[182:183], v[156:157], v[170:171], v[182:183]
	v_pk_fma_f32 v[184:185], v[156:157], v[174:175], v[184:185]
	v_pk_fma_f32 v[212:213], v[156:157], v[178:179], v[212:213]
	s_cbranch_scc1 .LBB0_809
	s_nop 0
	v_add_f32_e32 v102, v180, v181
	v_add_f32_e32 v103, v182, v183
	v_add_f32_e32 v104, v184, v185
	v_add_f32_e32 v105, v212, v213
	global_load_dword v133, v[46:47], off offset:2048
	s_waitcnt vmcnt(0)
	v_fmamk_f32 v102, v133, 0xbfb8aa3b, v102
	v_fmac_f32_e32 v103, 0xbfb8aa3b, v133
	v_fmamk_f32 v104, v133, 0xbfb8aa3b, v104
	v_fmac_f32_e32 v105, 0xbfb8aa3b, v133
	ds_write_b32 v115, v102 offset:6144
	ds_write_b32 v115, v103 offset:10368
	ds_write_b32 v115, v104 offset:14592
	ds_write_b32 v115, v105 offset:18816

; __device__ __forceinline__ void fox_sample_unit(const Params& p, int l, int b, int h, float* sf) {
;     ...
;                 const int key = tid >> 2, tq = tid & 3;
;                 if (key < nk) {
;                     float acc[4] = {0.f, 0.f, 0.f, 0.f};
; #pragma unroll 4
;                     for (int d4 = 0; d4 < 16; ++d4) { const f32x4 kv = *(const f32x4*)(sT + key * 68 + d4 * 4);
; #pragma unroll
;                         for (int i = 0; i < 4; ++i) { const f32x4 qv = *(const f32x4*)(sQ + (tq * 4 + i) * 64 + d4 * 4); acc[i] += (kv.x * qv.x + kv.y * qv.y) + (kv.z * qv.z + kv.w * qv.w); } }
;                     const int gkey = tile * 128 + key; const float bias = -CKS[gkey] * LOG2E;
; #pragma unroll
;                     for (int i = 0; i < 4; ++i) { const int t = tq * 4 + i; float s = acc[i] + bias; if (gkey > 1024 + t) s = -INFINITY; sS[t * 1056 + gkey] = s; }
.LBB0_824:
	v_add_u32_e32 v133, s58, v119
	v_add_u32_e32 v166, s58, v167
	v_add_u32_e32 v133, 0x11800, v133
	ds_read_b128 v[134:137], v133 offset:0
	ds_read_b128 v[138:141], v166 offset:0
	ds_read_b128 v[142:145], v166 offset:272
	ds_read_b128 v[146:149], v166 offset:544
	ds_read_b128 v[150:153], v166 offset:816
	ds_read_b128 v[154:157], v133 offset:16
	ds_read_b128 v[158:161], v166 offset:16
	ds_read_b128 v[168:171], v166 offset:288
	ds_read_b128 v[172:175], v166 offset:560
	ds_read_b128 v[176:179], v166 offset:832
	s_add_i32 s58, s58, 64
	s_cmpk_lg_i32 s58, 0x100
	s_waitcnt lgkmcnt(5)
	v_pk_fma_f32 v[180:181], v[134:135], v[138:139], v[180:181]
	v_pk_fma_f32 v[182:183], v[134:135], v[142:143], v[182:183]
	v_pk_fma_f32 v[184:185], v[134:135], v[146:147], v[184:185]
	v_pk_fma_f32 v[212:213], v[134:135], v[150:151], v[212:213]
	v_pk_fma_f32 v[180:181], v[136:137], v[140:141], v[180:181]
	v_pk_fma_f32 v[182:183], v[136:137], v[144:145], v[182:183]
	v_pk_fma_f32 v[184:185], v[136:137], v[148:149], v[184:185]
	v_pk_fma_f32 v[212:213], v[136:137], v[152:153], v[212:213]
	ds_read_b128 v[134:137], v133 offset:32
	ds_read_b128 v[138:141], v166 offset:32
	ds_read_b128 v[142:145], v166 offset:304
	ds_read_b128 v[146:149], v166 offset:576
	ds_read_b128 v[150:153], v166 offset:848
	s_waitcnt lgkmcnt(5)
	v_pk_fma_f32 v[180:181], v[154:155], v[158:159], v[180:181]
	v_pk_fma_f32 v[182:183], v[154:155], v[168:169], v[182:183]
	v_pk_fma_f32 v[184:185], v[154:155], v[172:173], v[184:185]
	v_pk_fma_f32 v[212:213], v[154:155], v[176:177], v[212:213]
	v_pk_fma_f32 v[180:181], v[156:157], v[160:161], v[180:181]
	v_pk_fma_f32 v[182:183], v[156:157], v[170:171], v[182:183]
	v_pk_fma_f32 v[184:185], v[156:157], v[174:175], v[184:185]
	v_pk_fma_f32 v[212:213], v[156:157], v[178:179], v[212:213]
	ds_read_b128 v[154:157], v133 offset:48
	ds_read_b128 v[158:161], v166 offset:48
	ds_read_b128 v[168:171], v166 offset:320
	ds_read_b128 v[172:175], v166 offset:592
	ds_read_b128 v[176:179], v166 offset:864
	s_waitcnt lgkmcnt(5)
	v_pk_fma_f32 v[180:181], v[134:135], v[138:139], v[180:181]
	v_pk_fma_f32 v[182:183], v[134:135], v[142:143], v[182:183]
	v_pk_fma_f32 v[184:185], v[134:135], v[146:147], v[184:185]
	v_pk_fma_f32 v[212:213], v[134:135], v[150:151], v[212:213]
	v_pk_fma_f32 v[180:181], v[136:137], v[140:141], v[180:181]
	v_pk_fma_f32 v[182:183], v[136:137], v[144:145], v[182:183]
	v_pk_fma_f32 v[184:185], v[136:137], v[148:149], v[184:185]
	v_pk_fma_f32 v[212:213], v[136:137], v[152:153], v[212:213]
	s_waitcnt lgkmcnt(0)
	v_pk_fma_f32 v[180:181], v[154:155], v[158:159], v[180:181]
	v_pk_fma_f32 v[182:183], v[154:155], v[168:169], v[182:183]
	v_pk_fma_f32 v[184:185], v[154:155], v[172:173], v[184:185]
	v_pk_fma_f32 v[212:213], v[154:155], v[176:177], v[212:213]
	v_pk_fma_f32 v[180:181], v[156:157], v[160:161], v[180:181]
	v_pk_fma_f32 v[182:183], v[156:157], v[170:171], v[182:183]
	v_pk_fma_f32 v[184:185], v[156:157], v[174:175], v[184:185]
	v_pk_fma_f32 v[212:213], v[156:157], v[178:179], v[212:213]
	s_cbranch_scc1 .LBB0_824
	s_nop 0
	v_add_f32_e32 v100, v180, v181
	v_add_f32_e32 v101, v182, v183
	v_add_f32_e32 v104, v184, v185
	v_add_f32_e32 v105, v212, v213
	global_load_dword v133, v[46:47], off offset:2560
	s_waitcnt vmcnt(0)
	v_fmamk_f32 v100, v133, 0xbfb8aa3b, v100
	v_fmac_f32_e32 v101, 0xbfb8aa3b, v133
	v_fmamk_f32 v104, v133, 0xbfb8aa3b, v104
	v_fmac_f32_e32 v105, 0xbfb8aa3b, v133
	ds_write_b32 v115, v100 offset:6656
	ds_write_b32 v115, v101 offset:10880
	ds_write_b32 v115, v104 offset:15104
	ds_write_b32 v115, v105 offset:19328

; __device__ __forceinline__ void fox_sample_unit(const Params& p, int l, int b, int h, float* sf) {
;     ...
;                 const int key = tid >> 2, tq = tid & 3;
;                 if (key < nk) {
;                     float acc[4] = {0.f, 0.f, 0.f, 0.f};
; #pragma unroll 4
;                     for (int d4 = 0; d4 < 16; ++d4) { const f32x4 kv = *(const f32x4*)(sT + key * 68 + d4 * 4);
; #pragma unroll
;                         for (int i = 0; i < 4; ++i) { const f32x4 qv = *(const f32x4*)(sQ + (tq * 4 + i) * 64 + d4 * 4); acc[i] += (kv.x * qv.x + kv.y * qv.y) + (kv.z * qv.z + kv.w * qv.w); } }
;                     const int gkey = tile * 128 + key; const float bias = -CKS[gkey] * LOG2E;
; #pragma unroll
;                     for (int i = 0; i < 4; ++i) { const int t = tq * 4 + i; float s = acc[i] + bias; if (gkey > 1024 + t) s = -INFINITY; sS[t * 1056 + gkey] = s; }
.LBB0_839:
	v_add_u32_e32 v133, s58, v119
	v_add_u32_e32 v156, s58, v167
	v_add_u32_e32 v133, 0x11800, v133
	ds_read_b128 v[134:137], v133 offset:0
	ds_read_b128 v[138:141], v156 offset:0
	ds_read_b128 v[142:145], v156 offset:272
	ds_read_b128 v[146:149], v156 offset:544
	ds_read_b128 v[150:153], v156 offset:816
	ds_read_b128 v[158:161], v133 offset:16
	ds_read_b128 v[168:171], v156 offset:16
	ds_read_b128 v[172:175], v156 offset:288
	ds_read_b128 v[176:179], v156 offset:560
	ds_read_b128 v[180:183], v156 offset:832
	s_add_i32 s58, s58, 64
	s_cmpk_lg_i32 s58, 0x100
	s_waitcnt lgkmcnt(5)
	v_pk_fma_f32 v[104:105], v[134:135], v[138:139], v[104:105]
	v_pk_fma_f32 v[154:155], v[134:135], v[142:143], v[154:155]
	v_pk_fma_f32 v[184:185], v[134:135], v[146:147], v[184:185]
	v_pk_fma_f32 v[212:213], v[134:135], v[150:151], v[212:213]
	v_pk_fma_f32 v[104:105], v[136:137], v[140:141], v[104:105]
	v_pk_fma_f32 v[154:155], v[136:137], v[144:145], v[154:155]
	v_pk_fma_f32 v[184:185], v[136:137], v[148:149], v[184:185]
	v_pk_fma_f32 v[212:213], v[136:137], v[152:153], v[212:213]
	ds_read_b128 v[134:137], v133 offset:32
	ds_read_b128 v[138:141], v156 offset:32
	ds_read_b128 v[142:145], v156 offset:304
	ds_read_b128 v[146:149], v156 offset:576
	ds_read_b128 v[150:153], v156 offset:848
	s_waitcnt lgkmcnt(5)
	v_pk_fma_f32 v[104:105], v[158:159], v[168:169], v[104:105]
	v_pk_fma_f32 v[154:155], v[158:159], v[172:173], v[154:155]
	v_pk_fma_f32 v[184:185], v[158:159], v[176:177], v[184:185]
	v_pk_fma_f32 v[212:213], v[158:159], v[180:181], v[212:213]
	v_pk_fma_f32 v[104:105], v[160:161], v[170:171], v[104:105]
	v_pk_fma_f32 v[154:155], v[160:161], v[174:175], v[154:155]
	v_pk_fma_f32 v[184:185], v[160:161], v[178:179], v[184:185]
	v_pk_fma_f32 v[212:213], v[160:161], v[182:183], v[212:213]
	ds_read_b128 v[158:161], v133 offset:48
	ds_read_b128 v[168:171], v156 offset:48
	ds_read_b128 v[172:175], v156 offset:320
	ds_read_b128 v[176:179], v156 offset:592
	ds_read_b128 v[180:183], v156 offset:864
	s_waitcnt lgkmcnt(5)
	v_pk_fma_f32 v[104:105], v[134:135], v[138:139], v[104:105]
	v_pk_fma_f32 v[154:155], v[134:135], v[142:143], v[154:155]
	v_pk_fma_f32 v[184:185], v[134:135], v[146:147], v[184:185]
	v_pk_fma_f32 v[212:213], v[134:135], v[150:151], v[212:213]
	v_pk_fma_f32 v[104:105], v[136:137], v[140:141], v[104:105]
	v_pk_fma_f32 v[154:155], v[136:137], v[144:145], v[154:155]
	v_pk_fma_f32 v[184:185], v[136:137], v[148:149], v[184:185]
	v_pk_fma_f32 v[212:213], v[136:137], v[152:153], v[212:213]
	s_waitcnt lgkmcnt(0)
	v_pk_fma_f32 v[104:105], v[158:159], v[168:169], v[104:105]
	v_pk_fma_f32 v[154:155], v[158:159], v[172:173], v[154:155]
	v_pk_fma_f32 v[184:185], v[158:159], v[176:177], v[184:185]
	v_pk_fma_f32 v[212:213], v[158:159], v[180:181], v[212:213]
	v_pk_fma_f32 v[104:105], v[160:161], v[170:171], v[104:105]
	v_pk_fma_f32 v[154:155], v[160:161], v[174:175], v[154:155]
	v_pk_fma_f32 v[184:185], v[160:161], v[178:179], v[184:185]
	v_pk_fma_f32 v[212:213], v[160:161], v[182:183], v[212:213]
	s_cbranch_scc1 .LBB0_839
	s_nop 0
	v_add_f32_e32 v98, v104, v105
	v_add_f32_e32 v99, v154, v155
	v_add_f32_e32 v102, v184, v185
	v_add_f32_e32 v103, v212, v213
	global_load_dword v104, v[46:47], off offset:3072
	s_waitcnt vmcnt(0)
	v_fmamk_f32 v98, v104, 0xbfb8aa3b, v98
	v_fmac_f32_e32 v99, 0xbfb8aa3b, v104
	v_fmamk_f32 v102, v104, 0xbfb8aa3b, v102
	v_fmac_f32_e32 v103, 0xbfb8aa3b, v104
	ds_write_b32 v115, v98 offset:7168
	ds_write_b32 v115, v99 offset:11392
	ds_write_b32 v115, v102 offset:15616
	ds_write_b32 v115, v103 offset:19840

; __device__ __forceinline__ void fox_sample_unit(const Params& p, int l, int b, int h, float* sf) {
;     ...
;                 const int key = tid >> 2, tq = tid & 3;
;                 if (key < nk) {
;                     float acc[4] = {0.f, 0.f, 0.f, 0.f};
; #pragma unroll 4
;                     for (int d4 = 0; d4 < 16; ++d4) { const f32x4 kv = *(const f32x4*)(sT + key * 68 + d4 * 4);
; #pragma unroll
;                         for (int i = 0; i < 4; ++i) { const f32x4 qv = *(const f32x4*)(sQ + (tq * 4 + i) * 64 + d4 * 4); acc[i] += (kv.x * qv.x + kv.y * qv.y) + (kv.z * qv.z + kv.w * qv.w); } }
;                     const int gkey = tile * 128 + key; const float bias = -CKS[gkey] * LOG2E;
; #pragma unroll
;                     for (int i = 0; i < 4; ++i) { const int t = tq * 4 + i; float s = acc[i] + bias; if (gkey > 1024 + t) s = -INFINITY; sS[t * 1056 + gkey] = s; }
.LBB0_859:
	v_add_u32_e32 v133, s58, v119
	v_add_u32_e32 v156, s58, v167
	v_add_u32_e32 v133, 0x11800, v133
	ds_read_b128 v[134:137], v133 offset:0
	ds_read_b128 v[138:141], v156 offset:0
	ds_read_b128 v[142:145], v156 offset:272
	ds_read_b128 v[146:149], v156 offset:544
	ds_read_b128 v[150:153], v156 offset:816
	ds_read_b128 v[158:161], v133 offset:16
	ds_read_b128 v[168:171], v156 offset:16
	ds_read_b128 v[172:175], v156 offset:288
	ds_read_b128 v[176:179], v156 offset:560
	ds_read_b128 v[180:183], v156 offset:832
	s_add_i32 s58, s58, 64
	s_cmpk_lg_i32 s58, 0x100
	s_waitcnt lgkmcnt(5)
	v_pk_fma_f32 v[104:105], v[134:135], v[138:139], v[104:105]
	v_pk_fma_f32 v[154:155], v[134:135], v[142:143], v[154:155]
	v_pk_fma_f32 v[184:185], v[134:135], v[146:147], v[184:185]
	v_pk_fma_f32 v[212:213], v[134:135], v[150:151], v[212:213]
	v_pk_fma_f32 v[104:105], v[136:137], v[140:141], v[104:105]
	v_pk_fma_f32 v[154:155], v[136:137], v[144:145], v[154:155]
	v_pk_fma_f32 v[184:185], v[136:137], v[148:149], v[184:185]
	v_pk_fma_f32 v[212:213], v[136:137], v[152:153], v[212:213]
	ds_read_b128 v[134:137], v133 offset:32
	ds_read_b128 v[138:141], v156 offset:32
	ds_read_b128 v[142:145], v156 offset:304
	ds_read_b128 v[146:149], v156 offset:576
	ds_read_b128 v[150:153], v156 offset:848
	s_waitcnt lgkmcnt(5)
	v_pk_fma_f32 v[104:105], v[158:159], v[168:169], v[104:105]
	v_pk_fma_f32 v[154:155], v[158:159], v[172:173], v[154:155]
	v_pk_fma_f32 v[184:185], v[158:159], v[176:177], v[184:185]
	v_pk_fma_f32 v[212:213], v[158:159], v[180:181], v[212:213]
	v_pk_fma_f32 v[104:105], v[160:161], v[170:171], v[104:105]
	v_pk_fma_f32 v[154:155], v[160:161], v[174:175], v[154:155]
	v_pk_fma_f32 v[184:185], v[160:161], v[178:179], v[184:185]
	v_pk_fma_f32 v[212:213], v[160:161], v[182:183], v[212:213]
	ds_read_b128 v[158:161], v133 offset:48
	ds_read_b128 v[168:171], v156 offset:48
	ds_read_b128 v[172:175], v156 offset:320
	ds_read_b128 v[176:179], v156 offset:592
	ds_read_b128 v[180:183], v156 offset:864
	s_waitcnt lgkmcnt(5)
	v_pk_fma_f32 v[104:105], v[134:135], v[138:139], v[104:105]
	v_pk_fma_f32 v[154:155], v[134:135], v[142:143], v[154:155]
	v_pk_fma_f32 v[184:185], v[134:135], v[146:147], v[184:185]
	v_pk_fma_f32 v[212:213], v[134:135], v[150:151], v[212:213]
	v_pk_fma_f32 v[104:105], v[136:137], v[140:141], v[104:105]
	v_pk_fma_f32 v[154:155], v[136:137], v[144:145], v[154:155]
	v_pk_fma_f32 v[184:185], v[136:137], v[148:149], v[184:185]
	v_pk_fma_f32 v[212:213], v[136:137], v[152:153], v[212:213]
	s_waitcnt lgkmcnt(0)
	v_pk_fma_f32 v[104:105], v[158:159], v[168:169], v[104:105]
	v_pk_fma_f32 v[154:155], v[158:159], v[172:173], v[154:155]
	v_pk_fma_f32 v[184:185], v[158:159], v[176:177], v[184:185]
	v_pk_fma_f32 v[212:213], v[158:159], v[180:181], v[212:213]
	v_pk_fma_f32 v[104:105], v[160:161], v[170:171], v[104:105]
	v_pk_fma_f32 v[154:155], v[160:161], v[174:175], v[154:155]
	v_pk_fma_f32 v[184:185], v[160:161], v[178:179], v[184:185]
	v_pk_fma_f32 v[212:213], v[160:161], v[182:183], v[212:213]
	s_cbranch_scc1 .LBB0_859
	s_nop 0
	v_add_f32_e32 v100, v104, v105
	v_add_f32_e32 v101, v154, v155
	v_add_f32_e32 v102, v184, v185
	v_add_f32_e32 v103, v212, v213
	global_load_dword v104, v[46:47], off offset:3584
	s_waitcnt vmcnt(0)
	v_fmamk_f32 v100, v104, 0xbfb8aa3b, v100
	v_fmac_f32_e32 v101, 0xbfb8aa3b, v104
	v_fmamk_f32 v102, v104, 0xbfb8aa3b, v102
	v_fmac_f32_e32 v103, 0xbfb8aa3b, v104
	ds_write_b32 v115, v100 offset:7680
	ds_write_b32 v115, v101 offset:11904
	ds_write_b32 v115, v102 offset:16128
	ds_write_b32 v115, v103 offset:20352

; __device__ __forceinline__ void fox_sample_unit(const Params& p, int l, int b, int h, float* sf) {
;     ...
;                 const int key = tid >> 2, tq = tid & 3;
;                 if (key < nk) {
;                     float acc[4] = {0.f, 0.f, 0.f, 0.f};
; #pragma unroll 4
;                     for (int d4 = 0; d4 < 16; ++d4) { const f32x4 kv = *(const f32x4*)(sT + key * 68 + d4 * 4);
; #pragma unroll
;                         for (int i = 0; i < 4; ++i) { const f32x4 qv = *(const f32x4*)(sQ + (tq * 4 + i) * 64 + d4 * 4); acc[i] += (kv.x * qv.x + kv.y * qv.y) + (kv.z * qv.z + kv.w * qv.w); } }
;                     const int gkey = tile * 128 + key; const float bias = -CKS[gkey] * LOG2E;
; #pragma unroll
;                     for (int i = 0; i < 4; ++i) { const int t = tq * 4 + i; float s = acc[i] + bias; if (gkey > 1024 + t) s = -INFINITY; sS[t * 1056 + gkey] = s; }
.LBB0_872:
	v_add_u32_e32 v133, s58, v119
	v_add_u32_e32 v6, 0x11800, v133
	v_add_u32_e32 v142, s58, v167
	ds_read_b128 v[6:9], v6
	ds_read_b128 v[10:13], v142 offset:0
	ds_read_b128 v[14:17], v142 offset:16
	ds_read_b128 v[102:105], v142 offset:32
	ds_read_b128 v[134:137], v142 offset:48
	ds_read_b128 v[138:141], v142 offset:272
	s_add_i32 s58, s58, 64
	s_cmpk_lg_i32 s58, 0x100
	s_waitcnt lgkmcnt(0)
	v_pk_mov_b32 v[98:99], v[10:11], v[138:139] op_sel:[1,0]
	v_mov_b32_e32 v11, v139
	v_pk_mul_f32 v[10:11], v[6:7], v[10:11]
	s_nop 0
	v_pk_fma_f32 v[10:11], v[6:7], v[98:99], v[10:11] op_sel:[1,0,0] op_sel_hi:[0,1,1]
	v_pk_mov_b32 v[98:99], v[12:13], v[140:141] op_sel:[1,0]
	v_mov_b32_e32 v13, v141
	v_pk_mul_f32 v[12:13], v[8:9], v[12:13]
	s_nop 0
	v_pk_fma_f32 v[12:13], v[8:9], v[98:99], v[12:13] op_sel:[1,0,0] op_sel_hi:[0,1,1]
	v_pk_add_f32 v[10:11], v[10:11], v[12:13]
	s_nop 0
	v_pk_add_f32 v[98:99], v[2:3], v[10:11]
	ds_read_b128 v[10:13], v142 offset:544
	s_waitcnt lgkmcnt(0)
	v_mul_f32_e32 v2, v7, v11
	v_pk_fma_f32 v[2:3], v[6:7], v[10:11], v[2:3] op_sel_hi:[1,1,0]
	v_mul_f32_e32 v10, v9, v13
	v_pk_fma_f32 v[138:139], v[8:9], v[12:13], v[10:11] op_sel_hi:[1,1,0]
	ds_read_b128 v[10:13], v142 offset:816
	s_waitcnt lgkmcnt(0)
	v_pk_mul_f32 v[8:9], v[8:9], v[12:13]
	v_pk_mul_f32 v[6:7], v[6:7], v[10:11]
	s_nop 0
	v_pk_mov_b32 v[10:11], v[6:7], v[8:9] op_sel:[1,0]
	v_mov_b32_e32 v7, v9
	v_pk_add_f32 v[6:7], v[10:11], v[6:7]
	s_nop 0
	v_mov_b32_e32 v3, v6
	v_mov_b32_e32 v139, v7
	v_pk_add_f32 v[2:3], v[2:3], v[138:139]
	s_nop 0
	v_pk_add_f32 v[10:11], v[4:5], v[2:3]
	v_add_u32_e32 v2, 0x11810, v133
	ds_read_b128 v[2:5], v2
	ds_read_b128 v[6:9], v142 offset:288
	s_waitcnt lgkmcnt(0)
	v_pk_mov_b32 v[12:13], v[14:15], v[6:7] op_sel:[1,0]
	v_mov_b32_e32 v15, v7
	v_pk_mul_f32 v[6:7], v[2:3], v[14:15]
	s_nop 0
	v_pk_fma_f32 v[6:7], v[2:3], v[12:13], v[6:7] op_sel:[1,0,0] op_sel_hi:[0,1,1]
	v_pk_mov_b32 v[12:13], v[16:17], v[8:9] op_sel:[1,0]
	v_mov_b32_e32 v17, v9
	v_pk_mul_f32 v[8:9], v[4:5], v[16:17]
	s_nop 0
	v_pk_fma_f32 v[8:9], v[4:5], v[12:13], v[8:9] op_sel:[1,0,0] op_sel_hi:[0,1,1]
	v_pk_add_f32 v[6:7], v[6:7], v[8:9]
	s_nop 0
	v_pk_add_f32 v[12:13], v[98:99], v[6:7]
	ds_read_b128 v[6:9], v142 offset:560
	s_waitcnt lgkmcnt(0)
	v_mul_f32_e32 v14, v3, v7
	v_pk_fma_f32 v[14:15], v[2:3], v[6:7], v[14:15] op_sel_hi:[1,1,0]
	v_mul_f32_e32 v6, v5, v9
	v_pk_fma_f32 v[16:17], v[4:5], v[8:9], v[6:7] op_sel_hi:[1,1,0]
	ds_read_b128 v[6:9], v142 offset:832
	s_waitcnt lgkmcnt(0)
	v_pk_mul_f32 v[4:5], v[4:5], v[8:9]
	v_pk_mul_f32 v[2:3], v[2:3], v[6:7]
	s_nop 0
	v_pk_mov_b32 v[6:7], v[2:3], v[4:5] op_sel:[1,0]
	v_mov_b32_e32 v3, v5
	v_pk_add_f32 v[2:3], v[6:7], v[2:3]
	s_nop 0
	v_mov_b32_e32 v15, v2
	v_mov_b32_e32 v17, v3
	v_pk_add_f32 v[2:3], v[14:15], v[16:17]
	s_nop 0
	v_pk_add_f32 v[10:11], v[10:11], v[2:3]
	v_add_u32_e32 v2, 0x11820, v133
	ds_read_b128 v[2:5], v2
	ds_read_b128 v[6:9], v142 offset:304
	s_waitcnt lgkmcnt(0)
	v_pk_mov_b32 v[14:15], v[102:103], v[6:7] op_sel:[1,0]
	v_mov_b32_e32 v103, v7
	v_pk_mul_f32 v[6:7], v[2:3], v[102:103]
	s_nop 0
	v_pk_fma_f32 v[6:7], v[2:3], v[14:15], v[6:7] op_sel:[1,0,0] op_sel_hi:[0,1,1]
	v_pk_mov_b32 v[14:15], v[104:105], v[8:9] op_sel:[1,0]
	v_mov_b32_e32 v105, v9
	v_pk_mul_f32 v[8:9], v[4:5], v[104:105]
	s_nop 0
	v_pk_fma_f32 v[8:9], v[4:5], v[14:15], v[8:9] op_sel:[1,0,0] op_sel_hi:[0,1,1]
	v_pk_add_f32 v[6:7], v[6:7], v[8:9]
	s_nop 0
	v_pk_add_f32 v[12:13], v[12:13], v[6:7]
	ds_read_b128 v[6:9], v142 offset:576
	s_waitcnt lgkmcnt(0)
	v_mul_f32_e32 v14, v3, v7
	v_pk_fma_f32 v[14:15], v[2:3], v[6:7], v[14:15] op_sel_hi:[1,1,0]
	v_mul_f32_e32 v6, v5, v9
	v_pk_fma_f32 v[16:17], v[4:5], v[8:9], v[6:7] op_sel_hi:[1,1,0]
	ds_read_b128 v[6:9], v142 offset:848
	s_waitcnt lgkmcnt(0)
	v_pk_mul_f32 v[4:5], v[4:5], v[8:9]
	v_pk_mul_f32 v[2:3], v[2:3], v[6:7]
	s_nop 0
	v_pk_mov_b32 v[6:7], v[2:3], v[4:5] op_sel:[1,0]
	v_mov_b32_e32 v3, v5
	v_pk_add_f32 v[2:3], v[6:7], v[2:3]
	s_nop 0
	v_mov_b32_e32 v15, v2
	v_mov_b32_e32 v17, v3
	v_pk_add_f32 v[2:3], v[14:15], v[16:17]
	s_nop 0
	v_pk_add_f32 v[14:15], v[10:11], v[2:3]
	v_add_u32_e32 v2, 0x11830, v133
	ds_read_b128 v[4:7], v2
	ds_read_b128 v[8:11], v142 offset:320
	s_waitcnt lgkmcnt(0)
	v_pk_mov_b32 v[2:3], v[134:135], v[8:9] op_sel:[1,0]
	v_mov_b32_e32 v135, v9
	v_pk_mul_f32 v[8:9], v[4:5], v[134:135]
	s_nop 0
	v_pk_fma_f32 v[2:3], v[4:5], v[2:3], v[8:9] op_sel:[1,0,0] op_sel_hi:[0,1,1]
	v_pk_mov_b32 v[8:9], v[136:137], v[10:11] op_sel:[1,0]
	v_mov_b32_e32 v137, v11
	v_pk_mul_f32 v[10:11], v[6:7], v[136:137]
	s_nop 0
	v_pk_fma_f32 v[8:9], v[6:7], v[8:9], v[10:11] op_sel:[1,0,0] op_sel_hi:[0,1,1]
	v_pk_add_f32 v[2:3], v[2:3], v[8:9]
	ds_read_b128 v[8:11], v142 offset:592
	v_pk_add_f32 v[2:3], v[12:13], v[2:3]
	s_waitcnt lgkmcnt(0)
	v_mul_f32_e32 v12, v5, v9
	v_pk_fma_f32 v[12:13], v[4:5], v[8:9], v[12:13] op_sel_hi:[1,1,0]
	v_mul_f32_e32 v8, v7, v11
	v_pk_fma_f32 v[16:17], v[6:7], v[10:11], v[8:9] op_sel_hi:[1,1,0]
	ds_read_b128 v[8:11], v142 offset:864
	s_waitcnt lgkmcnt(0)
	v_pk_mul_f32 v[6:7], v[6:7], v[10:11]
	v_pk_mul_f32 v[4:5], v[4:5], v[8:9]
	s_nop 0
	v_pk_mov_b32 v[8:9], v[4:5], v[6:7] op_sel:[1,0]
	v_mov_b32_e32 v5, v7
	v_pk_add_f32 v[4:5], v[8:9], v[4:5]
	s_nop 0
	v_mov_b32_e32 v13, v4
	v_mov_b32_e32 v17, v5
	v_pk_add_f32 v[4:5], v[12:13], v[16:17]
	s_nop 0
	v_pk_add_f32 v[4:5], v[14:15], v[4:5]
	s_cbranch_scc1 .LBB0_872
	global_load_dword v6, v[96:97], off
	s_waitcnt vmcnt(0)
	v_fmamk_f32 v2, v6, 0xbfb8aa3b, v2
	v_fmac_f32_e32 v3, 0xbfb8aa3b, v6
	v_fmamk_f32 v4, v6, 0xbfb8aa3b, v4
	v_fmac_f32_e32 v5, 0xbfb8aa3b, v6
	v_cndmask_b32_e64 v2, v2, v204, s[24:25]
	v_cndmask_b32_e64 v3, v3, v204, s[26:27]
	v_cndmask_b32_e64 v4, v4, v204, s[28:29]
	v_cndmask_b32_e64 v5, v5, v204, s[30:31]
	ds_write_b32 v115, v2 offset:8192
	ds_write_b32 v115, v3 offset:12416
	ds_write_b32 v115, v4 offset:16640
	ds_write_b32 v115, v5 offset:20864
